# nt also on the scan's GO2 output stores (written once, read once by the next phase)
# speedup vs baseline: 1.0066x; 1.0066x over previous
; #define GD_STORE_ROWS(cidx, buf) do { _Pragma("unroll") for (int i_ = 0; i_ < 2; ++i_) { const int id_ = F.tid + 512 * i_, row_ = id_ >> 4, ch_ = id_ & 15; \
;         const v4u v_ = *(const LAS v4u*)(ost + (buf) * 16384 + row_ * 256 + ((ch_ ^ (((row_ >> 2) & 3) << 2)) * 16)); \
;         *(v4u*)(GOb + (size_t)(b * TT + 64 * (cidx) + row_) * 1024 + h * 128 + ch_ * 8) = v_; } } while (0)
; __device__ __forceinline__ void gdn_scan_phase(const Frame& F0, const Args& a0, int nblk, bool last) {
;     ...
;         if (cprev >= 0 && !(last && cprev < 4)) GD_STORE_ROWS(cprev, (s + 1) & 1);
.LBB0_568:
	s_andn2_b32 s6, 0x4000, s19
	v_add_u32_e32 v38, s6, v102
	s_lshl_b32 s6, s27, 6
	v_add_u32_e32 v32, v38, v83
	s_add_i32 s6, s6, s18
	ds_read_b128 v[32:35], v32
	v_add_u32_e32 v36, s6, v82
	v_ashrrev_i32_e32 v37, 31, v36
	v_lshlrev_b64 v[36:37], 11, v[36:37]
	v_lshl_add_u64 v[36:37], v[64:65], 0, v[36:37]
	s_waitcnt lgkmcnt(0)
	global_store_dwordx4 v[36:37], v[32:35], off nt
	v_add_u32_e32 v36, s6, v69
	v_ashrrev_i32_e32 v37, 31, v36
	v_add_u32_e32 v32, v38, v81
	ds_read_b128 v[32:35], v32
	v_lshlrev_b64 v[36:37], 11, v[36:37]
	v_lshl_add_u64 v[36:37], v[64:65], 0, v[36:37]
	s_waitcnt lgkmcnt(0)
	global_store_dwordx4 v[36:37], v[32:35], off nt

; #define LAS __attribute__((address_space(3)))
; #define VM_WAIT() asm volatile("s_waitcnt vmcnt(0)" ::: "memory")
; #define GD_STORE_ROWS(cidx, buf) do { _Pragma("unroll") for (int i_ = 0; i_ < 2; ++i_) { const int id_ = F.tid + 512 * i_, row_ = id_ >> 4, ch_ = id_ & 15; \
;         const v4u v_ = *(const LAS v4u*)(ost + (buf) * 16384 + row_ * 256 + ((ch_ ^ (((row_ >> 2) & 3) << 2)) * 16)); \
;         *(v4u*)(GOb + (size_t)(b * TT + 64 * (cidx) + row_) * 1024 + h * 128 + ch_ * 8) = v_; } } while (0)
; #define GD_LOAD8(dst, f0) do { _Pragma("unroll") for (int i_ = 0; i_ < 8; ++i_) dst[i_] = GD_FRAG((f0) + i_); } while (0)
; #define GD_PIN() __builtin_amdgcn_sched_barrier(0)
; __device__ __forceinline__ void gdn_scan_phase(const Frame& F0, const Args& a0, int nblk, bool last) {
;     ...
;         if (cprev >= 0 && !(last && cprev < 4)) GD_STORE_ROWS(cprev, (s + 1) & 1);
;     ...
;         const LAS unsigned char* Bf = lds + (s & 1) * GD_REC + lane * 16;
;     ...
;         bf16x8 fA[8], fB[8], fC[8];
;     ...
;         GD_LOAD8(fA, 0); GD_LOAD8(fB, 8);
;         bf16x8 Sf[4];
; #pragma unroll
;         for (int kb = 0; kb < 4; ++kb) Sf[kb] = pack8(S[2 * kb], S[2 * kb + 1]);
;         f32x4 O[4];
; #pragma unroll
;         for (int mt = 0; mt < 4; ++mt) O[mt] = (f32x4){0.f, 0.f, 0.f, 0.f};
;         GD_PIN();
; #pragma unroll
;         for (int i = 0; i < 8; ++i) V[i >> 2] = __builtin_amdgcn_mfma_f32_16x16x32_bf16(fA[i], Sf[i & 3], V[i >> 2], 0, 0, 0);
;         GD_PIN(); GD_LOAD8(fC, 16); GD_PIN();
; #pragma unroll
;         for (int i = 0; i < 8; ++i) V[2 + (i >> 2)] = __builtin_amdgcn_mfma_f32_16x16x32_bf16(fB[i], Sf[i & 3], V[2 + (i >> 2)], 0, 0, 0);
;         GD_PIN(); GD_LOAD8(fA, 24); GD_PIN();
; #pragma unroll
;         for (int i = 0; i < 8; ++i) O[i >> 2] = __builtin_amdgcn_mfma_f32_16x16x32_bf16(fC[i], Sf[i & 3], O[i >> 2], 0, 0, 0);
;         GD_PIN(); GD_LOAD8(fB, 32); GD_PIN();
; #pragma unroll
;         for (int i = 0; i < 8; ++i) O[2 + (i >> 2)] = __builtin_amdgcn_mfma_f32_16x16x32_bf16(fA[i], Sf[i & 3], O[2 + (i >> 2)], 0, 0, 0);
;     ...
;         VM_WAIT(); __syncthreads();
.LBB0_574:
	s_waitcnt vmcnt(0)
	s_add_i32 s26, s26, -1
	s_addk_i32 s19, 0x4000
	s_cmp_eq_u32 s26, 3
	s_waitcnt vmcnt(0) lgkmcnt(0)
	s_barrier
	s_cbranch_scc0 .LBB0_567
	s_cmp_lt_i32 s27, s22
	s_cbranch_scc1 .LBB0_577
	s_lshl_b32 s0, s27, 6
	v_add_u32_e32 v48, v102, v83
	s_add_i32 s0, s0, s18
	ds_read_b128 v[48:51], v48
	v_add_u32_e32 v52, s0, v82
	v_ashrrev_i32_e32 v53, 31, v52
	v_lshlrev_b64 v[52:53], 11, v[52:53]
	v_lshl_add_u64 v[52:53], v[64:65], 0, v[52:53]
	s_waitcnt lgkmcnt(0)
	global_store_dwordx4 v[52:53], v[48:51], off nt
	v_add_u32_e32 v52, s0, v69
	v_ashrrev_i32_e32 v53, 31, v52
	v_add_u32_e32 v48, v102, v81
	ds_read_b128 v[48:51], v48
	v_lshlrev_b64 v[52:53], 11, v[52:53]
	v_lshl_add_u64 v[52:53], v[64:65], 0, v[52:53]
	s_waitcnt lgkmcnt(0)
	global_store_dwordx4 v[52:53], v[48:51], off nt
.LBB0_577:
	s_nop 1
	v_add_u32_e32 v48, 0x11c00, v101
	v_add_u32_e32 v52, 0x11800, v101
	v_add_u32_e32 v56, 0x11400, v101
	v_add_u32_e32 v60, 0x11000, v101
	v_add_u32_e32 v70, 0x10c00, v101
	v_add_u32_e32 v74, 0x10800, v101
	v_add_u32_e32 v78, 0x10400, v101
	ds_read_b128 v[48:51], v48
	ds_read_b128 v[52:55], v52
	ds_read_b128 v[56:59], v56
	ds_read_b128 v[60:63], v60
	ds_read_b128 v[70:73], v70
	ds_read_b128 v[74:77], v74
	v_add_u32_e32 v79, 0x10000, v101
	ds_read_b128 v[102:105], v78
	ds_read_b128 v[106:109], v79
	ds_read_b128 v[110:113], v101 offset:64512
	ds_read_b128 v[114:117], v101 offset:63488
	ds_read_b128 v[118:121], v101 offset:62464
	ds_read_b128 v[122:125], v101 offset:61440
	ds_read_b128 v[126:129], v101 offset:60416
	ds_read_b128 v[130:133], v101 offset:59392
	ds_read_b128 v[134:137], v101 offset:58368
	ds_read_b128 v[138:141], v101 offset:57344
	s_and_b64 s[0:1], s[4:5], exec
	s_movk_i32 s0, 0x8c0
	s_cselect_b32 s0, s0, 0x100
	v_cvt_pk_bf16_f32 v28, v28, v29
	v_cvt_pk_bf16_f32 v29, v30, v31
	v_cvt_pk_bf16_f32 v30, v24, v25
	v_cvt_pk_bf16_f32 v31, v26, v27
	v_cvt_pk_bf16_f32 v20, v20, v21
	v_cvt_pk_bf16_f32 v21, v22, v23
	v_cvt_pk_bf16_f32 v22, v16, v17
	v_cvt_pk_bf16_f32 v23, v18, v19
	v_cvt_pk_bf16_f32 v12, v12, v13
	v_cvt_pk_bf16_f32 v13, v14, v15
	v_cvt_pk_bf16_f32 v14, v8, v9
	v_cvt_pk_bf16_f32 v15, v10, v11
	v_cvt_pk_bf16_f32 v4, v4, v5
	v_cvt_pk_bf16_f32 v5, v6, v7
	v_cvt_pk_bf16_f32 v6, v0, v1
	v_cvt_pk_bf16_f32 v7, v2, v3
	s_waitcnt lgkmcnt(0)
	v_mfma_f32_16x16x32_bf16 v[0:3], v[138:141], v[28:31], v[44:47]
	v_mfma_f32_16x16x32_bf16 v[8:11], v[122:125], v[28:31], v[40:43]
	v_mfma_f32_16x16x32_bf16 v[0:3], v[134:137], v[20:23], v[0:3]
	v_mfma_f32_16x16x32_bf16 v[8:11], v[118:121], v[20:23], v[8:11]
	v_mfma_f32_16x16x32_bf16 v[0:3], v[130:133], v[12:15], v[0:3]
	v_mfma_f32_16x16x32_bf16 v[8:11], v[114:117], v[12:15], v[8:11]
	v_mfma_f32_16x16x32_bf16 v[0:3], v[126:129], v[4:7], v[0:3]
	v_mfma_f32_16x16x32_bf16 v[8:11], v[110:113], v[4:7], v[8:11]
	v_add_u32_e32 v16, 0x12000, v101
	v_add_u32_e32 v24, 0x12400, v101
	v_add_u32_e32 v40, 0x12800, v101
	v_add_u32_e32 v44, 0x12c00, v101
	v_add_u32_e32 v78, 0x13000, v101
	ds_read_b128 v[16:19], v16
	ds_read_b128 v[24:27], v24
	ds_read_b128 v[40:43], v40
	ds_read_b128 v[44:47], v44
	v_add_u32_e32 v79, 0x13400, v101
	ds_read_b128 v[110:113], v78
	ds_read_b128 v[114:117], v79
	v_add_u32_e32 v78, 0x13800, v101
	v_add_u32_e32 v79, 0x13c00, v101
	ds_read_b128 v[118:121], v78
	ds_read_b128 v[122:125], v79
	v_mfma_f32_16x16x32_bf16 v[36:39], v[106:109], v[28:31], v[36:39]
	v_mfma_f32_16x16x32_bf16 v[32:35], v[60:63], v[28:31], v[32:35]
	v_mfma_f32_16x16x32_bf16 v[36:39], v[102:105], v[20:23], v[36:39]
	v_mfma_f32_16x16x32_bf16 v[32:35], v[56:59], v[20:23], v[32:35]
	v_mfma_f32_16x16x32_bf16 v[36:39], v[74:77], v[12:15], v[36:39]
	v_mfma_f32_16x16x32_bf16 v[32:35], v[52:55], v[12:15], v[32:35]
	v_mfma_f32_16x16x32_bf16 v[36:39], v[70:73], v[4:7], v[36:39]
	v_mfma_f32_16x16x32_bf16 v[32:35], v[48:51], v[4:7], v[32:35]
	v_add_u32_e32 v48, 0x14000, v101
	v_add_u32_e32 v52, 0x14400, v101
	v_add_u32_e32 v56, 0x14800, v101
	v_add_u32_e32 v60, 0x14c00, v101
	v_add_u32_e32 v70, 0x15000, v101
	v_add_u32_e32 v74, 0x15400, v101
	v_add_u32_e32 v78, 0x15800, v101
	ds_read_b128 v[48:51], v48
	ds_read_b128 v[52:55], v52
	ds_read_b128 v[56:59], v56
	ds_read_b128 v[60:63], v60
	ds_read_b128 v[70:73], v70
	ds_read_b128 v[74:77], v74
	v_add_u32_e32 v79, 0x15c00, v101
	ds_read_b128 v[102:105], v78
	ds_read_b128 v[106:109], v79
	s_waitcnt lgkmcnt(14)
	v_mfma_f32_16x16x32_bf16 v[16:19], v[16:19], v[28:31], 0
	v_mfma_f32_16x16x32_bf16 v[16:19], v[24:27], v[20:23], v[16:19]
	s_waitcnt lgkmcnt(11)
	v_mfma_f32_16x16x32_bf16 v[24:27], v[110:113], v[28:31], 0
	s_waitcnt lgkmcnt(10)
	v_mfma_f32_16x16x32_bf16 v[24:27], v[114:117], v[20:23], v[24:27]
	v_mfma_f32_16x16x32_bf16 v[16:19], v[40:43], v[12:15], v[16:19]
	s_waitcnt lgkmcnt(9)
	v_mfma_f32_16x16x32_bf16 v[24:27], v[118:121], v[12:15], v[24:27]
	v_mfma_f32_16x16x32_bf16 v[16:19], v[44:47], v[4:7], v[16:19]
	s_waitcnt lgkmcnt(8)
	v_mfma_f32_16x16x32_bf16 v[24:27], v[122:125], v[4:7], v[24:27]
	s_waitcnt lgkmcnt(7)
	v_mfma_f32_16x16x32_bf16 v[40:43], v[48:51], v[28:31], 0
	s_waitcnt lgkmcnt(3)
	v_mfma_f32_16x16x32_bf16 v[28:31], v[70:73], v[28:31], 0
	v_mfma_f32_16x16x32_bf16 v[40:43], v[52:55], v[20:23], v[40:43]
	s_waitcnt lgkmcnt(2)
	v_mfma_f32_16x16x32_bf16 v[20:23], v[74:77], v[20:23], v[28:31]
	v_mfma_f32_16x16x32_bf16 v[40:43], v[56:59], v[12:15], v[40:43]
	s_waitcnt lgkmcnt(1)
; __device__ __forceinline__ void gdn_scan_phase(const Frame& F0, const Args& a0, int nblk, bool last) {
;     ...
;         for (int i = 0; i < 8; ++i) O[i >> 2] = __builtin_amdgcn_mfma_f32_16x16x32_bf16(fC[i], Sf[i & 3], O[i >> 2], 0, 0, 0);
;         GD_PIN(); GD_LOAD8(fB, 32); GD_PIN();
; #pragma unroll
;         for (int i = 0; i < 8; ++i) O[2 + (i >> 2)] = __builtin_amdgcn_mfma_f32_16x16x32_bf16(fA[i], Sf[i & 3], O[2 + (i >> 2)], 0, 0, 0);
;         GD_PIN(); GD_LOAD8(fC, 40); GD_PIN();
;         bf16x8 Vf[2]; Vf[0] = pack8(V[0], V[1]); Vf[1] = pack8(V[2], V[3]);
; #pragma unroll
;         for (int t = 0; t < 8; ++t) S[t] = S[t] * gl;
; #pragma unroll
;         for (int i = 0; i < 8; ++i) S[i >> 1] = __builtin_amdgcn_mfma_f32_16x16x32_bf16(fB[i], Vf[i & 1], S[i >> 1], 0, 0, 0);
;         GD_PIN();
; #pragma unroll
;         for (int i_ = 0; i_ < 8; ++i_) if (i_ != 1 && i_ != 3) fA[i_] = GD_FRAG(48 + i_);
;         GD_PIN();
; #pragma unroll
;         for (int i = 0; i < 8; ++i) S[4 + (i >> 1)] = __builtin_amdgcn_mfma_f32_16x16x32_bf16(fC[i], Vf[i & 1], S[4 + (i >> 1)], 0, 0, 0);
; #pragma unroll
;         for (int i = 0; i < 8; ++i) if (i != 1 && i != 3) O[i >> 1] = __builtin_amdgcn_mfma_f32_16x16x32_bf16(fA[i], Vf[i & 1], O[i >> 1], 0, 0, 0);
;     ...
;         if (!(last && c < 4)) {
;             LAS unsigned char* ob = ost + (s & 1) * 16384;
;             const bool ev = !(cc & 1);
; #pragma unroll
;             for (int mt = 0; mt < 4; ++mt) {
;                 const float s0 = ev ? O[mt][2] : O[mt][0], s1 = ev ? O[mt][3] : O[mt][1];
;                 const float r0 = __builtin_bit_cast(float, __builtin_amdgcn_mov_dpp(__builtin_bit_cast(int, s0), 0xB1, 0xF, 0xF, true));
;                 const float r1 = __builtin_bit_cast(float, __builtin_amdgcn_mov_dpp(__builtin_bit_cast(int, s1), 0xB1, 0xF, 0xF, true));
;                 const unsigned w0 = ev ? pk2(O[mt][0], r0) : pk2(r0, O[mt][2]), w1 = ev ? pk2(O[mt][1], r1) : pk2(r1, O[mt][3]);
; #pragma unroll
;                 for (int e = 0; e < 2; ++e) { const int p = 16 * mt + 4 * g + (ev ? 0 : 2) + e, tok = d ? 63 - p : p;
;                     *(LAS unsigned*)(ob + tok * 256 + (((2 * n + (cc >> 3)) ^ (((tok >> 2) & 3) << 2)) * 16) + (cc & 6) * 2) = e ? w1 : w0; } }
;         }
;         cprev = c;
;         if (REP_SLEEP) __builtin_amdgcn_s_sleep(REP_SLEEP);
;         VM_WAIT(); __syncthreads();
;     }
	v_mfma_f32_16x16x32_bf16 v[12:15], v[102:105], v[12:15], v[20:23]
	v_mfma_f32_16x16x32_bf16 v[40:43], v[60:63], v[4:7], v[40:43]
	s_waitcnt lgkmcnt(0)
	v_mfma_f32_16x16x32_bf16 v[4:7], v[106:109], v[4:7], v[12:15]
	v_cvt_pk_bf16_f32 v0, v0, v1
	v_cvt_pk_bf16_f32 v1, v2, v3
	v_cvt_pk_bf16_f32 v2, v8, v9
	v_cvt_pk_bf16_f32 v3, v10, v11
	v_cvt_pk_bf16_f32 v8, v36, v37
	v_cvt_pk_bf16_f32 v9, v38, v39
	v_cvt_pk_bf16_f32 v10, v32, v33
	v_cvt_pk_bf16_f32 v11, v34, v35
	v_add_u32_e32 v12, 0x1a000, v101
	v_add_u32_e32 v20, 0x1a800, v101
	v_add_u32_e32 v28, 0x1b000, v101
	v_add_u32_e32 v32, 0x1b400, v101
	v_add_u32_e32 v36, 0x1b800, v101
	v_add_u32_e32 v44, 0x1bc00, v101
	ds_read_b128 v[12:15], v12
	ds_read_b128 v[20:23], v20
	ds_read_b128 v[28:31], v28
	ds_read_b128 v[32:35], v32
	ds_read_b128 v[36:39], v36
	ds_read_b128 v[44:47], v44
	s_waitcnt lgkmcnt(5)
	v_mfma_f32_16x16x32_bf16 v[12:15], v[12:15], v[0:3], v[16:19]
	v_cmp_eq_u32_e32 vcc, 1, v68
	v_cmp_eq_u32_e64 s[4:5], 2, v68
	v_cmp_eq_u32_e64 s[6:7], 3, v68
	v_cmp_eq_u32_e64 s[8:9], 1, v66
	v_cmp_eq_u32_e64 s[10:11], 2, v66
	s_nop 2
	v_cndmask_b32_e32 v16, v12, v13, vcc
	v_cndmask_b32_e64 v48, v16, v14, s[4:5]
	s_waitcnt lgkmcnt(4)
	v_mfma_f32_16x16x32_bf16 v[16:19], v[20:23], v[0:3], v[24:27]
	v_cndmask_b32_e64 v20, v48, v15, s[6:7]
	v_cmp_eq_u32_e64 s[14:15], 3, v66
	s_add_i32 s1, 0, 0x20000
	v_mov_b32_dpp v24, v20 quad_perm:[1,0,3,2] row_mask:0xf bank_mask:0xf bound_ctrl:1
	v_cndmask_b32_e64 v25, v12, v13, s[8:9]
	s_waitcnt lgkmcnt(3)
	v_mfma_f32_16x16x32_bf16 v[20:23], v[28:31], v[0:3], v[40:43]
	v_cndmask_b32_e64 v25, v25, v14, s[10:11]
	v_cndmask_b32_e64 v25, v25, v15, s[14:15]
	s_add_i32 s0, s0, s18
	s_waitcnt lgkmcnt(1)
	v_mfma_f32_16x16x32_bf16 v[0:3], v[36:39], v[0:3], v[4:7]
	v_mov_b32_dpp v25, v25 quad_perm:[1,0,3,2] row_mask:0xf bank_mask:0xf bound_ctrl:1
	v_readlane_b32 s24, v220, 26
	s_mov_b32 s74, 0xf800000
	v_cndmask_b32_e64 v4, v24, v12, s[2:3]
	v_cndmask_b32_e64 v5, v14, v24, s[2:3]
	v_cvt_pk_bf16_f32 v4, v4, v5
	v_add_u32_e32 v5, s1, v97
	v_add3_u32 v5, v5, v98, v84
	v_cndmask_b32_e64 v6, v25, v13, s[2:3]
	v_cndmask_b32_e64 v7, v15, v25, s[2:3]
	ds_write_b32 v5, v4
	v_add_u32_e32 v5, s1, v99
	v_cvt_pk_bf16_f32 v4, v6, v7
	v_add3_u32 v5, v5, v100, v84
	ds_write_b32 v5, v4
	v_cndmask_b32_e32 v4, v16, v17, vcc
	v_cndmask_b32_e64 v4, v4, v18, s[4:5]
	v_cndmask_b32_e64 v4, v4, v19, s[6:7]
	v_cndmask_b32_e64 v5, v16, v17, s[8:9]
	v_cndmask_b32_e64 v5, v5, v18, s[10:11]
	v_mov_b32_dpp v4, v4 quad_perm:[1,0,3,2] row_mask:0xf bank_mask:0xf bound_ctrl:1
	v_cndmask_b32_e64 v5, v5, v19, s[14:15]
	v_cndmask_b32_e64 v6, v4, v16, s[2:3]
	v_cndmask_b32_e64 v4, v18, v4, s[2:3]
	v_mfma_f32_16x16x32_bf16 v[20:23], v[32:35], v[8:11], v[20:23]
	v_mov_b32_dpp v5, v5 quad_perm:[1,0,3,2] row_mask:0xf bank_mask:0xf bound_ctrl:1
	v_cvt_pk_bf16_f32 v4, v6, v4
	v_add_u32_e32 v6, s1, v93
	v_cndmask_b32_e64 v7, v5, v17, s[2:3]
	v_cndmask_b32_e64 v5, v19, v5, s[2:3]
	v_add3_u32 v6, v6, v94, v84
	ds_write_b32 v6, v4
	v_cvt_pk_bf16_f32 v4, v7, v5
	v_add_u32_e32 v5, s1, v95
	v_add3_u32 v5, v5, v96, v84
	ds_write_b32 v5, v4
	v_cndmask_b32_e32 v4, v20, v21, vcc
	v_cndmask_b32_e64 v4, v4, v22, s[4:5]
	v_cndmask_b32_e64 v4, v4, v23, s[6:7]
	v_cndmask_b32_e64 v5, v20, v21, s[8:9]
	v_cndmask_b32_e64 v5, v5, v22, s[10:11]
	v_mov_b32_dpp v4, v4 quad_perm:[1,0,3,2] row_mask:0xf bank_mask:0xf bound_ctrl:1
	v_cndmask_b32_e64 v5, v5, v23, s[14:15]
	v_cndmask_b32_e64 v6, v4, v20, s[2:3]
	v_cndmask_b32_e64 v4, v22, v4, s[2:3]
	s_waitcnt lgkmcnt(4)
	v_mfma_f32_16x16x32_bf16 v[0:3], v[44:47], v[8:11], v[0:3]
	v_mov_b32_dpp v5, v5 quad_perm:[1,0,3,2] row_mask:0xf bank_mask:0xf bound_ctrl:1
	v_cvt_pk_bf16_f32 v4, v6, v4
	v_add_u32_e32 v6, s1, v89
	v_cndmask_b32_e64 v7, v5, v21, s[2:3]
	v_cndmask_b32_e64 v5, v23, v5, s[2:3]
	v_add3_u32 v6, v6, v90, v84
	ds_write_b32 v6, v4
	v_cvt_pk_bf16_f32 v4, v7, v5
	v_add_u32_e32 v5, s1, v91
	v_add3_u32 v5, v5, v92, v84
	ds_write_b32 v5, v4
	v_cndmask_b32_e32 v4, v0, v1, vcc
	v_cndmask_b32_e64 v4, v4, v2, s[4:5]
	v_cndmask_b32_e64 v4, v4, v3, s[6:7]
	v_cndmask_b32_e64 v5, v0, v1, s[8:9]
	v_cndmask_b32_e64 v5, v5, v2, s[10:11]
	v_mov_b32_dpp v4, v4 quad_perm:[1,0,3,2] row_mask:0xf bank_mask:0xf bound_ctrl:1
	v_cndmask_b32_e64 v5, v5, v3, s[14:15]
	v_cndmask_b32_e64 v0, v4, v0, s[2:3]
	v_cndmask_b32_e64 v2, v2, v4, s[2:3]
	v_mov_b32_dpp v5, v5 quad_perm:[1,0,3,2] row_mask:0xf bank_mask:0xf bound_ctrl:1
	v_cvt_pk_bf16_f32 v0, v0, v2
	v_add_u32_e32 v2, s1, v85
	v_cndmask_b32_e64 v1, v5, v1, s[2:3]
	v_cndmask_b32_e64 v3, v3, v5, s[2:3]
	v_add3_u32 v2, v2, v86, v84
	ds_write_b32 v2, v0
	v_cvt_pk_bf16_f32 v0, v1, v3
	v_add_u32_e32 v1, s1, v87
	v_add3_u32 v1, v1, v88, v84
	v_add_u32_e32 v6, s1, v67
	ds_write_b32 v1, v0
	v_add_u32_e32 v0, v6, v83
	s_waitcnt vmcnt(0)
	s_waitcnt lgkmcnt(0)
	s_barrier
	ds_read_b128 v[0:3], v0
	v_add_u32_e32 v4, s0, v82
	v_ashrrev_i32_e32 v5, 31, v4
	v_lshlrev_b64 v[4:5], 11, v[4:5]
	v_lshl_add_u64 v[8:9], v[64:65], 0, v[4:5]
	v_add_u32_e32 v4, v6, v81
	ds_read_b128 v[4:7], v4
	s_waitcnt lgkmcnt(1)
	global_store_dwordx4 v[8:9], v[0:3], off nt
	s_mov_b64 s[88:89], 0x40000
	v_readlane_b32 s25, v220, 27
	v_add_u32_e32 v0, s0, v69
	v_ashrrev_i32_e32 v1, 31, v0
	v_lshlrev_b64 v[0:1], 11, v[0:1]
	v_lshl_add_u64 v[0:1], v[64:65], 0, v[0:1]
	v_readlane_b32 s75, v220, 25
	s_waitcnt lgkmcnt(0)
	global_store_dwordx4 v[0:1], v[4:7], off nt
